# v3 plus: trailing half (waves 4-7) raised right after its re-stagger barrier at the tile boundary, so its tile header and first load segment run prioritized beside the leading half's first MMA
# speedup vs baseline: 1.0055x; 1.0055x over previous
; #define BAR __builtin_amdgcn_s_barrier()
; template <int BMODE, class Epi, class TileFn>
; DEV void gemm_loop(LAS unsigned char* lds, const bf16_t* __restrict__ A, int lda, const bf16_t* __restrict__ B, int ldb, int K, const Epi& epi, int t0, int tstep, int tend, const TileFn& tf) {
;     ...
;         if (!has_next) break;
; #pragma unroll
;         for (int a = 0; a < 2; ++a)
; #pragma unroll
;             for (int b = 0; b < 2; ++b)
; #pragma unroll
;                 for (int m = 0; m < 4; ++m)
; #pragma unroll
;                     for (int n = 0; n < 2; ++n) acc[a][b][m][n] = (f32x4){0.f, 0.f, 0.f, 0.f};
;         brow = nrow; bcol = ncol; cA = nA; cB = nB;
;         if (wr == 1) BAR;
;     }
.LBB0_514:
	s_and_saveexec_b64 s[8:9], s[38:39]
	s_cbranch_execz .LBB0_434
	s_barrier
	s_setprio 1
	s_branch .LBB0_434

; #define BAR __builtin_amdgcn_s_barrier()
; template <int BMODE, class Epi, class TileFn>
; DEV void gemm_loop(LAS unsigned char* lds, const bf16_t* __restrict__ A, int lda, const bf16_t* __restrict__ B, int ldb, int K, const Epi& epi, int t0, int tstep, int tend, const TileFn& tf) {
;     ...
;         if (!has_next) break;
; #pragma unroll
;         for (int a = 0; a < 2; ++a)
; #pragma unroll
;             for (int b = 0; b < 2; ++b)
; #pragma unroll
;                 for (int m = 0; m < 4; ++m)
; #pragma unroll
;                     for (int n = 0; n < 2; ++n) acc[a][b][m][n] = (f32x4){0.f, 0.f, 0.f, 0.f};
;         brow = nrow; bcol = ncol; cA = nA; cB = nB;
;         if (wr == 1) BAR;
;     }
.LBB0_1260:
	s_or_b64 exec, exec, s[0:1]
	s_andn2_b64 vcc, exec, s[40:41]
	s_mov_b64 s[0:1], -1
	s_cbranch_vccnz .LBB0_1235
	s_and_saveexec_b64 s[0:1], s[42:43]
	s_xor_b64 s[0:1], exec, s[0:1]
	s_cbranch_execz .LBB0_1234
	s_barrier
	s_setprio 1
	s_branch .LBB0_1234

; #define LAS __attribute__((address_space(3)))
; DEV u32x4 pack8(const float (&v)[8]) { u32x4 w; w.x = cvt_pk_bf16(v[0], v[1]); w.y = cvt_pk_bf16(v[2], v[3]); w.z = cvt_pk_bf16(v[4], v[5]); w.w = cvt_pk_bf16(v[6], v[7]); return w; }
; DEV void TileMap::operator()(int t, int& brow, int& bcol) const { int pm, pn; tile_map(t, nM, nN, pm, pn); brow = pm * 256; bcol = pn * 256; }
; DEV void TileG1::operator()(int t, int& brow, int& bcol) const { int pm, pn; tile_map(t, 192, 7, pm, pn); brow = pm * 256; bcol = (pn == 0 ? 6 : pn - 1) * 256; }
; DEV void TileMapRev::operator()(int t, int& brow, int& bcol) const { int pm, pn; tile_map(t, nM, nN, pm, pn); brow = (nM - 1 - pm) * 256; bcol = pn * 256; }
;     DEV void operator()(f32x4 (&acc)[2][2][4][2], int brow, int bcol, LAS unsigned char* lds, int par) const {
;         EPI_IDS
; #pragma unroll
;         for (int ai = 0; ai < 2; ++ai)
; #pragma unroll
;             for (int m = 0; m < 4; ++m) {
;                 const int lr = ai * 128 + wr * 64 + m * 16 + fr, row = brow + lr;
;                 const f32x4 s4 = *(const LAS f32x4*)(lds + LDS_EX + par * 4096 + lr * 16);
;                 const float rs = rsqrtf(((s4[0] + s4[1]) + (s4[2] + s4[3])) * (1.0f / 1024.0f) + EPS);
;                 float o[8];
;                 const float rs2 = rs * rs, ce = rs * -1.4426950408889634f;
; #pragma unroll
;                 for (int bj = 0; bj < 2; ++bj) {
;                     const f32x4 g = acc[ai][bj][m][0], u = acc[ai][bj][m][1];
; #pragma unroll
;                     for (int j = 0; j < 4; ++j) o[bj * 4 + j] = (g[j] * u[j]) * rs2 * __builtin_amdgcn_rcpf(1.0f + __builtin_amdgcn_exp2f(g[j] * ce));
;                 }
;                 *(u32x4*)(act + (size_t)row * DFF + (bcol >> 1) + wc * 32 + fq * 8) = pack8(o);
.LBB0_1341:
	s_or_b64 exec, exec, s[8:9]
	v_mov_b32_e32 v137, v188
	s_movk_i32 s8, 0xffc0
	v_and_b32_e32 v136, 15, v137
	v_ashrrev_i32_e32 v138, 2, v137
	v_and_or_b32 v136, v138, s8, v136
	s_lshl_b32 s8, s4, 12
	s_add_i32 s8, s8, 0
	s_add_i32 s8, s8, 0x20000
	v_lshl_add_u32 v138, v136, 4, s8
	ds_read_b128 v[158:161], v138
	v_mul_f32_e32 v120, v124, v120
	v_mul_f32_e32 v121, v125, v121
	v_mul_f32_e32 v122, v126, v122
	v_mul_f32_e32 v123, v127, v123
	s_waitcnt lgkmcnt(0)
	v_mov_b32_e32 v138, v159
	v_mov_b32_e32 v139, v160
	v_mov_b32_e32 v159, v161
	v_pk_add_f32 v[138:139], v[138:139], v[158:159]
	v_mul_f32_e32 v159, v116, v112
	v_add_f32_e32 v138, v138, v139
	v_fmamk_f32 v138, v138, 0x3a800000, v189
	v_cmp_gt_f32_e32 vcc, s24, v138
	v_mul_f32_e32 v139, 0x4b800000, v138
	v_mul_f32_e32 v160, v117, v113
	v_cndmask_b32_e32 v138, v138, v139, vcc
	v_rsq_f32_e32 v138, v138
	s_ashr_i32 s30, s29, 1
	s_ashr_i32 s31, s30, 31
	s_lshl_b64 s[54:55], s[30:31], 1
	v_mul_f32_e32 v139, 0x45800000, v138
	v_cndmask_b32_e32 v139, v138, v139, vcc
	v_mul_f32_e32 v158, 0xbfb8aa3b, v139
	v_mul_f32_e32 v112, v116, v158
	v_exp_f32_e32 v112, v112
	v_mov_b32_e32 v138, v118
	v_mul_f32_e32 v118, v118, v158
	v_exp_f32_e32 v118, v118
	v_add_f32_e32 v112, 1.0, v112
	v_rcp_f32_e32 v116, v112
	v_mul_f32_e32 v112, v117, v158
	v_exp_f32_e32 v112, v112
	v_add_f32_e32 v118, 1.0, v118
	v_rcp_f32_e32 v118, v118
	v_mov_b32_e32 v113, v139
	v_add_f32_e32 v112, 1.0, v112
	v_rcp_f32_e32 v117, v112
	v_mov_b32_e32 v112, v114
	v_pk_mul_f32 v[112:113], v[138:139], v[112:113]
	v_mul_f32_e32 v124, v124, v158
	v_mul_f32_e32 v112, v112, v113
	v_mul_f32_e32 v114, v120, v113
	v_mul_f32_e32 v120, v121, v113
	v_mul_f32_e32 v121, v122, v113
	v_mul_f32_e32 v122, v123, v113
	v_mul_f32_e32 v123, v159, v113
	v_mul_f32_e32 v118, v112, v118
	v_mul_f32_e32 v112, v119, v115
	v_exp_f32_e32 v124, v124
	v_mul_f32_e32 v125, v125, v158
	v_mul_f32_e32 v116, v123, v116
	v_mul_f32_e32 v123, v160, v113
	v_mul_f32_e32 v112, v112, v113
	v_mul_f32_e32 v113, v119, v158
	v_exp_f32_e32 v125, v125
	v_exp_f32_e32 v113, v113
	v_mul_f32_e32 v126, v126, v158
	v_exp_f32_e32 v126, v126
	v_mul_f32_e32 v127, v127, v158
	v_add_f32_e32 v124, 1.0, v124
	v_exp_f32_e32 v127, v127
	v_rcp_f32_e32 v124, v124
	v_add_f32_e32 v125, 1.0, v125
	v_add_f32_e32 v113, 1.0, v113
	v_rcp_f32_e32 v125, v125
	v_rcp_f32_e32 v113, v113
	v_add_f32_e32 v126, 1.0, v126
	v_rcp_f32_e32 v126, v126
	v_add_f32_e32 v127, 1.0, v127
	v_rcp_f32_e32 v127, v127
	v_mul_f32_e32 v114, v114, v124
	v_mul_f32_e32 v117, v123, v117
	v_mul_f32_e32 v120, v120, v125
	v_mul_f32_e32 v115, v112, v113
	v_add_u32_e32 v119, s28, v136
	v_cvt_pk_bf16_f32 v112, v114, v120
	v_cvt_pk_bf16_f32 v114, v116, v117
	v_mov_b64_e32 v[116:117], s[70:71]
	v_cvt_pk_bf16_f32 v115, v118, v115
	v_mad_i64_i32 v[118:119], s[36:37], v119, s33, v[116:117]
	v_mul_f32_e32 v121, v121, v126
	v_lshl_add_u64 v[118:119], v[118:119], 0, s[54:55]
	v_and_b32_e32 v194, 0xc0, v137
	v_mul_f32_e32 v122, v122, v127
	v_cvt_pk_bf16_f32 v113, v121, v122
	v_lshl_add_u64 v[120:121], v[118:119], 0, v[194:195]
	v_and_b32_e32 v118, 48, v137
	v_mov_b32_e32 v119, v195
	v_lshl_add_u64 v[120:121], v[120:121], 0, v[118:119]
	global_store_dwordx4 v[120:121], v[112:115], off
	v_or_b32_e32 v120, 16, v136
	v_mul_f32_e32 v100, v96, v100
	v_lshl_add_u32 v112, v120, 4, s8
	ds_read_b128 v[112:115], v112
	v_mul_f32_e32 v108, v104, v108
	v_mul_f32_e32 v109, v105, v109
	v_mul_f32_e32 v110, v106, v110
	v_mul_f32_e32 v111, v107, v111
	s_waitcnt lgkmcnt(0)
	v_mov_b32_e32 v122, v113
	v_mov_b32_e32 v123, v114
	v_mov_b32_e32 v113, v115
	v_pk_add_f32 v[112:113], v[122:123], v[112:113]
	v_mul_f32_e32 v101, v97, v101
	v_add_f32_e32 v112, v112, v113
	v_fmamk_f32 v112, v112, 0x3a800000, v189
	v_cmp_gt_f32_e32 vcc, s24, v112
	v_mul_f32_e32 v113, 0x4b800000, v112
	v_mul_f32_e32 v88, v92, v88
	v_cndmask_b32_e32 v112, v112, v113, vcc
	v_rsq_f32_e32 v112, v112
	v_mul_f32_e32 v89, v93, v89
	v_mul_f32_e32 v90, v94, v90
	v_mul_f32_e32 v91, v95, v91
	v_mul_f32_e32 v113, 0x45800000, v112
	v_cndmask_b32_e32 v113, v112, v113, vcc
	v_mul_f32_e32 v114, 0xbfb8aa3b, v113
	v_mul_f32_e32 v96, v96, v114
	v_exp_f32_e32 v96, v96
	v_mul_f32_e32 v104, v104, v114
	v_exp_f32_e32 v104, v104
	v_mul_f32_e32 v105, v105, v114
	v_add_f32_e32 v96, 1.0, v96
	v_rcp_f32_e32 v115, v96
	v_mul_f32_e32 v96, v97, v114
	v_exp_f32_e32 v105, v105
	v_mul_f32_e32 v106, v106, v114
	v_exp_f32_e32 v96, v96
	v_exp_f32_e32 v106, v106
	v_mul_f32_e32 v107, v107, v114
	v_mov_b32_e32 v112, v98
	v_mul_f32_e32 v98, v98, v114
	v_exp_f32_e32 v107, v107
	v_exp_f32_e32 v98, v98
	v_add_f32_e32 v104, 1.0, v104
	v_rcp_f32_e32 v104, v104
	v_add_f32_e32 v105, 1.0, v105
	v_add_f32_e32 v96, 1.0, v96
	v_rcp_f32_e32 v105, v105
	v_add_f32_e32 v106, 1.0, v106
	v_rcp_f32_e32 v121, v96
	v_mov_b32_e32 v96, v102
	v_mov_b32_e32 v97, v113
	v_rcp_f32_e32 v106, v106
	v_add_f32_e32 v107, 1.0, v107
	v_pk_mul_f32 v[96:97], v[112:113], v[96:97]
	v_add_f32_e32 v98, 1.0, v98
	v_rcp_f32_e32 v107, v107
	v_mul_f32_e32 v102, v108, v97
	v_rcp_f32_e32 v98, v98
	v_mul_f32_e32 v102, v102, v104
	v_mul_f32_e32 v104, v109, v97
	v_mul_f32_e32 v104, v104, v105
	v_mul_f32_e32 v105, v110, v97
	v_mul_f32_e32 v105, v105, v106
	v_mul_f32_e32 v106, v111, v97
	v_mul_f32_e32 v96, v96, v97
	v_mul_f32_e32 v106, v106, v107
	v_mul_f32_e32 v107, v96, v98
	v_mul_f32_e32 v96, v99, v103
	v_mul_f32_e32 v100, v100, v97
	v_mul_f32_e32 v101, v101, v97
	v_mul_f32_e32 v96, v96, v97
	v_mul_f32_e32 v97, v99, v114
	v_exp_f32_e32 v97, v97
	v_mul_f32_e32 v100, v100, v115
	v_mul_f32_e32 v101, v101, v121
	v_add_u32_e32 v103, s28, v120
	v_add_f32_e32 v97, 1.0, v97
	v_rcp_f32_e32 v97, v97
	v_cvt_pk_bf16_f32 v98, v100, v101
	v_mad_i64_i32 v[100:101], s[30:31], v103, s33, v[116:117]
	v_lshl_add_u64 v[100:101], v[100:101], 0, s[54:55]
	v_lshl_add_u64 v[100:101], v[100:101], 0, v[194:195]
	v_mul_f32_e32 v99, v96, v97
	v_cvt_pk_bf16_f32 v96, v102, v104
	v_lshl_add_u64 v[100:101], v[100:101], 0, v[118:119]
	v_or_b32_e32 v102, 32, v136
	v_cvt_pk_bf16_f32 v97, v105, v106
	v_cvt_pk_bf16_f32 v99, v107, v99
	global_store_dwordx4 v[100:101], v[96:99], off
	v_mul_f32_e32 v68, v64, v68
	v_mul_f32_e32 v76, v72, v76
	v_lshl_add_u32 v96, v102, 4, s8
	ds_read_b128 v[96:99], v96
	v_mul_f32_e32 v77, v73, v77
	v_mul_f32_e32 v78, v74, v78
	v_mul_f32_e32 v79, v75, v79
	v_mul_f32_e32 v69, v65, v69
	s_waitcnt lgkmcnt(0)
; #define LAS __attribute__((address_space(3)))
; DEV u32x4 pack8(const float (&v)[8]) { u32x4 w; w.x = cvt_pk_bf16(v[0], v[1]); w.y = cvt_pk_bf16(v[2], v[3]); w.z = cvt_pk_bf16(v[4], v[5]); w.w = cvt_pk_bf16(v[6], v[7]); return w; }
; DEV void TileMap::operator()(int t, int& brow, int& bcol) const { int pm, pn; tile_map(t, nM, nN, pm, pn); brow = pm * 256; bcol = pn * 256; }
; DEV void TileG1::operator()(int t, int& brow, int& bcol) const { int pm, pn; tile_map(t, 192, 7, pm, pn); brow = pm * 256; bcol = (pn == 0 ? 6 : pn - 1) * 256; }
; DEV void TileMapRev::operator()(int t, int& brow, int& bcol) const { int pm, pn; tile_map(t, nM, nN, pm, pn); brow = (nM - 1 - pm) * 256; bcol = pn * 256; }
;     DEV void operator()(f32x4 (&acc)[2][2][4][2], int brow, int bcol, LAS unsigned char* lds, int par) const {
;         EPI_IDS
; #pragma unroll
;         for (int ai = 0; ai < 2; ++ai)
; #pragma unroll
;             for (int m = 0; m < 4; ++m) {
;                 const int lr = ai * 128 + wr * 64 + m * 16 + fr, row = brow + lr;
;                 const f32x4 s4 = *(const LAS f32x4*)(lds + LDS_EX + par * 4096 + lr * 16);
;                 const float rs = rsqrtf(((s4[0] + s4[1]) + (s4[2] + s4[3])) * (1.0f / 1024.0f) + EPS);
;                 float o[8];
;                 const float rs2 = rs * rs, ce = rs * -1.4426950408889634f;
; #pragma unroll
;                 for (int bj = 0; bj < 2; ++bj) {
;                     const f32x4 g = acc[ai][bj][m][0], u = acc[ai][bj][m][1];
; #pragma unroll
;                     for (int j = 0; j < 4; ++j) o[bj * 4 + j] = (g[j] * u[j]) * rs2 * __builtin_amdgcn_rcpf(1.0f + __builtin_amdgcn_exp2f(g[j] * ce));
;                 }
;                 *(u32x4*)(act + (size_t)row * DFF + (bcol >> 1) + wc * 32 + fq * 8) = pack8(o);
	v_mov_b32_e32 v100, v97
	v_mov_b32_e32 v101, v98
	v_mov_b32_e32 v97, v99
	v_pk_add_f32 v[96:97], v[100:101], v[96:97]
	v_mul_f32_e32 v99, v84, v80
	v_add_f32_e32 v96, v96, v97
	v_fmamk_f32 v96, v96, 0x3a800000, v189
	v_cmp_gt_f32_e32 vcc, s24, v96
	v_mul_f32_e32 v97, 0x4b800000, v96
	v_mul_f32_e32 v100, v85, v81
	v_cndmask_b32_e32 v96, v96, v97, vcc
	v_rsq_f32_e32 v96, v96
	v_mul_f32_e32 v56, v60, v56
	v_mul_f32_e32 v57, v61, v57
	v_mul_f32_e32 v58, v62, v58
	v_mul_f32_e32 v97, 0x45800000, v96
	v_cndmask_b32_e32 v97, v96, v97, vcc
	v_mul_f32_e32 v98, 0xbfb8aa3b, v97
	v_mul_f32_e32 v80, v84, v98
	v_exp_f32_e32 v80, v80
	v_mov_b32_e32 v96, v86
	v_mul_f32_e32 v86, v86, v98
	v_exp_f32_e32 v86, v86
	v_add_f32_e32 v80, 1.0, v80
	v_rcp_f32_e32 v84, v80
	v_mul_f32_e32 v80, v85, v98
	v_exp_f32_e32 v80, v80
	v_add_f32_e32 v86, 1.0, v86
	v_rcp_f32_e32 v86, v86
	v_mov_b32_e32 v81, v97
	v_add_f32_e32 v80, 1.0, v80
	v_rcp_f32_e32 v85, v80
	v_mov_b32_e32 v80, v82
	v_pk_mul_f32 v[80:81], v[96:97], v[80:81]
	v_mul_f32_e32 v92, v92, v98
	v_mul_f32_e32 v80, v80, v81
	v_mul_f32_e32 v82, v88, v81
	v_mul_f32_e32 v88, v89, v81
	v_mul_f32_e32 v89, v90, v81
	v_mul_f32_e32 v90, v91, v81
	v_mul_f32_e32 v91, v99, v81
	v_mul_f32_e32 v86, v80, v86
	v_mul_f32_e32 v80, v87, v83
	v_exp_f32_e32 v92, v92
	v_mul_f32_e32 v93, v93, v98
	v_mul_f32_e32 v84, v91, v84
	v_mul_f32_e32 v91, v100, v81
	v_mul_f32_e32 v80, v80, v81
	v_mul_f32_e32 v81, v87, v98
	v_exp_f32_e32 v93, v93
	v_exp_f32_e32 v81, v81
	v_add_f32_e32 v92, 1.0, v92
	v_mul_f32_e32 v94, v94, v98
	v_mul_f32_e32 v95, v95, v98
	v_rcp_f32_e32 v92, v92
	v_add_f32_e32 v93, 1.0, v93
	v_exp_f32_e32 v94, v94
	v_exp_f32_e32 v95, v95
	v_add_f32_e32 v81, 1.0, v81
	v_rcp_f32_e32 v93, v93
	v_rcp_f32_e32 v81, v81
	v_add_f32_e32 v94, 1.0, v94
	v_add_f32_e32 v95, 1.0, v95
	v_mul_f32_e32 v82, v82, v92
	v_mul_f32_e32 v85, v91, v85
	v_add_u32_e32 v87, s28, v102
	v_rcp_f32_e32 v94, v94
	v_rcp_f32_e32 v95, v95
	v_mul_f32_e32 v88, v88, v93
	v_mul_f32_e32 v83, v80, v81
	v_cvt_pk_bf16_f32 v80, v82, v88
	v_cvt_pk_bf16_f32 v82, v84, v85
	v_mad_i64_i32 v[84:85], s[30:31], v87, s33, v[116:117]
	v_lshl_add_u64 v[84:85], v[84:85], 0, s[54:55]
	v_lshl_add_u64 v[84:85], v[84:85], 0, v[194:195]
	v_cvt_pk_bf16_f32 v83, v86, v83
	v_lshl_add_u64 v[84:85], v[84:85], 0, v[118:119]
	v_or_b32_e32 v86, 48, v136
	v_mul_f32_e32 v89, v89, v94
	v_mul_f32_e32 v90, v90, v95
	v_cvt_pk_bf16_f32 v81, v89, v90
	global_store_dwordx4 v[84:85], v[80:83], off
	v_mul_f32_e32 v59, v63, v59
	v_mul_f32_e32 v36, v32, v36
	v_lshl_add_u32 v80, v86, 4, s8
	ds_read_b128 v[80:83], v80
	v_mul_f32_e32 v44, v40, v44
	v_mul_f32_e32 v45, v41, v45
	v_mul_f32_e32 v46, v42, v46
	v_mul_f32_e32 v47, v43, v47
	s_waitcnt lgkmcnt(0)
	v_mov_b32_e32 v84, v81
	v_mov_b32_e32 v85, v82
	v_mov_b32_e32 v81, v83
	v_pk_add_f32 v[80:81], v[84:85], v[80:81]
	v_mul_f32_e32 v37, v33, v37
	v_add_f32_e32 v80, v80, v81
	v_fmamk_f32 v80, v80, 0x3a800000, v189
	v_cmp_gt_f32_e32 vcc, s24, v80
	v_mul_f32_e32 v81, 0x4b800000, v80
	v_mul_f32_e32 v24, v28, v24
	v_cndmask_b32_e32 v80, v80, v81, vcc
	v_rsq_f32_e32 v80, v80
	v_mul_f32_e32 v25, v29, v25
	v_mul_f32_e32 v26, v30, v26
	v_mul_f32_e32 v27, v31, v27
	v_mul_f32_e32 v81, 0x45800000, v80
	v_cndmask_b32_e32 v81, v80, v81, vcc
	v_mul_f32_e32 v82, 0xbfb8aa3b, v81
	v_mul_f32_e32 v64, v64, v82
	v_exp_f32_e32 v64, v64
	v_mul_f32_e32 v72, v72, v82
	v_exp_f32_e32 v72, v72
	v_mul_f32_e32 v73, v73, v82
	v_add_f32_e32 v64, 1.0, v64
	v_rcp_f32_e32 v83, v64
	v_mul_f32_e32 v64, v65, v82
	v_exp_f32_e32 v73, v73
	v_mul_f32_e32 v74, v74, v82
	v_exp_f32_e32 v64, v64
	v_exp_f32_e32 v74, v74
	v_mul_f32_e32 v75, v75, v82
	v_mov_b32_e32 v80, v66
	v_mul_f32_e32 v66, v66, v82
	v_exp_f32_e32 v75, v75
	v_exp_f32_e32 v66, v66
	v_add_f32_e32 v72, 1.0, v72
	v_rcp_f32_e32 v72, v72
	v_add_f32_e32 v73, 1.0, v73
	v_add_f32_e32 v64, 1.0, v64
	v_rcp_f32_e32 v73, v73
	v_add_f32_e32 v74, 1.0, v74
	v_rcp_f32_e32 v84, v64
	v_mov_b32_e32 v64, v70
	v_mov_b32_e32 v65, v81
	v_rcp_f32_e32 v74, v74
	v_add_f32_e32 v75, 1.0, v75
	v_pk_mul_f32 v[64:65], v[80:81], v[64:65]
	v_add_f32_e32 v66, 1.0, v66
	v_rcp_f32_e32 v75, v75
	v_mul_f32_e32 v70, v76, v65
	v_rcp_f32_e32 v66, v66
	v_mul_f32_e32 v70, v70, v72
	v_mul_f32_e32 v72, v77, v65
	v_mul_f32_e32 v72, v72, v73
	v_mul_f32_e32 v73, v78, v65
	v_mul_f32_e32 v73, v73, v74
	v_mul_f32_e32 v74, v79, v65
	v_mul_f32_e32 v64, v64, v65
	v_mul_f32_e32 v74, v74, v75
	v_mul_f32_e32 v75, v64, v66
	v_mul_f32_e32 v64, v67, v71
	v_mul_f32_e32 v68, v68, v65
	v_mul_f32_e32 v69, v69, v65
	v_mul_f32_e32 v64, v64, v65
	v_mul_f32_e32 v65, v67, v82
	v_exp_f32_e32 v65, v65
	v_mul_f32_e32 v68, v68, v83
	v_mul_f32_e32 v69, v69, v84
	v_add_u32_e32 v71, s28, v86
	v_add_f32_e32 v65, 1.0, v65
	v_rcp_f32_e32 v65, v65
	v_cvt_pk_bf16_f32 v66, v68, v69
	v_mad_i64_i32 v[68:69], s[30:31], v71, s33, v[116:117]
	v_lshl_add_u64 v[68:69], v[68:69], 0, s[54:55]
	v_lshl_add_u64 v[68:69], v[68:69], 0, v[194:195]
	v_mul_f32_e32 v67, v64, v65
	v_cvt_pk_bf16_f32 v64, v70, v72
	v_lshl_add_u64 v[68:69], v[68:69], 0, v[118:119]
	v_add_u32_e32 v70, 0x80, v136
	v_cvt_pk_bf16_f32 v65, v73, v74
	v_cvt_pk_bf16_f32 v67, v75, v67
	global_store_dwordx4 v[68:69], v[64:67], off
	v_mul_f32_e32 v4, v0, v4
	v_mul_f32_e32 v12, v8, v12
	v_lshl_add_u32 v64, v70, 4, s8
	ds_read_b128 v[64:67], v64
	v_mul_f32_e32 v13, v9, v13
	v_mul_f32_e32 v14, v10, v14
	v_mul_f32_e32 v15, v11, v15
	v_mul_f32_e32 v5, v1, v5
	s_waitcnt lgkmcnt(0)
; #define LAS __attribute__((address_space(3)))
; DEV u32x4 pack8(const float (&v)[8]) { u32x4 w; w.x = cvt_pk_bf16(v[0], v[1]); w.y = cvt_pk_bf16(v[2], v[3]); w.z = cvt_pk_bf16(v[4], v[5]); w.w = cvt_pk_bf16(v[6], v[7]); return w; }
; DEV void TileMap::operator()(int t, int& brow, int& bcol) const { int pm, pn; tile_map(t, nM, nN, pm, pn); brow = pm * 256; bcol = pn * 256; }
; DEV void TileG1::operator()(int t, int& brow, int& bcol) const { int pm, pn; tile_map(t, 192, 7, pm, pn); brow = pm * 256; bcol = (pn == 0 ? 6 : pn - 1) * 256; }
; DEV void TileMapRev::operator()(int t, int& brow, int& bcol) const { int pm, pn; tile_map(t, nM, nN, pm, pn); brow = (nM - 1 - pm) * 256; bcol = pn * 256; }
;     DEV void operator()(f32x4 (&acc)[2][2][4][2], int brow, int bcol, LAS unsigned char* lds, int par) const {
;         EPI_IDS
; #pragma unroll
;         for (int ai = 0; ai < 2; ++ai)
; #pragma unroll
;             for (int m = 0; m < 4; ++m) {
;                 const int lr = ai * 128 + wr * 64 + m * 16 + fr, row = brow + lr;
;                 const f32x4 s4 = *(const LAS f32x4*)(lds + LDS_EX + par * 4096 + lr * 16);
;                 const float rs = rsqrtf(((s4[0] + s4[1]) + (s4[2] + s4[3])) * (1.0f / 1024.0f) + EPS);
;                 float o[8];
;                 const float rs2 = rs * rs, ce = rs * -1.4426950408889634f;
; #pragma unroll
;                 for (int bj = 0; bj < 2; ++bj) {
;                     const f32x4 g = acc[ai][bj][m][0], u = acc[ai][bj][m][1];
; #pragma unroll
;                     for (int j = 0; j < 4; ++j) o[bj * 4 + j] = (g[j] * u[j]) * rs2 * __builtin_amdgcn_rcpf(1.0f + __builtin_amdgcn_exp2f(g[j] * ce));
;                 }
;                 *(u32x4*)(act + (size_t)row * DFF + (bcol >> 1) + wc * 32 + fq * 8) = pack8(o);
	v_mov_b32_e32 v68, v65
	v_mov_b32_e32 v69, v66
	v_mov_b32_e32 v65, v67
	v_pk_add_f32 v[64:65], v[68:69], v[64:65]
	v_mul_f32_e32 v67, v52, v48
	v_add_f32_e32 v64, v64, v65
	v_fmamk_f32 v64, v64, 0x3a800000, v189
	v_cmp_gt_f32_e32 vcc, s24, v64
	v_mul_f32_e32 v65, 0x4b800000, v64
	v_mul_f32_e32 v68, v53, v49
	v_cndmask_b32_e32 v64, v64, v65, vcc
	v_rsq_f32_e32 v64, v64
	v_readlane_b32 s97, v250, 13
	v_mul_f32_e32 v65, 0x45800000, v64
	v_cndmask_b32_e32 v65, v64, v65, vcc
	v_mul_f32_e32 v66, 0xbfb8aa3b, v65
	v_mul_f32_e32 v48, v52, v66
	v_exp_f32_e32 v48, v48
	v_mov_b32_e32 v64, v54
	v_mul_f32_e32 v54, v54, v66
	v_exp_f32_e32 v54, v54
	v_add_f32_e32 v48, 1.0, v48
	v_rcp_f32_e32 v52, v48
	v_mul_f32_e32 v48, v53, v66
	v_exp_f32_e32 v48, v48
	v_add_f32_e32 v54, 1.0, v54
	v_rcp_f32_e32 v54, v54
	v_mov_b32_e32 v49, v65
	v_add_f32_e32 v48, 1.0, v48
	v_rcp_f32_e32 v53, v48
	v_mov_b32_e32 v48, v50
	v_pk_mul_f32 v[48:49], v[64:65], v[48:49]
	v_mul_f32_e32 v60, v60, v66
	v_mul_f32_e32 v48, v48, v49
	v_mul_f32_e32 v50, v56, v49
	v_mul_f32_e32 v56, v57, v49
	v_mul_f32_e32 v57, v58, v49
	v_mul_f32_e32 v58, v59, v49
	v_mul_f32_e32 v59, v67, v49
	v_mul_f32_e32 v54, v48, v54
	v_mul_f32_e32 v48, v55, v51
	v_exp_f32_e32 v60, v60
	v_mul_f32_e32 v61, v61, v66
	v_mul_f32_e32 v52, v59, v52
	v_mul_f32_e32 v59, v68, v49
	v_mul_f32_e32 v48, v48, v49
	v_mul_f32_e32 v49, v55, v66
	v_exp_f32_e32 v61, v61
	v_exp_f32_e32 v49, v49
	v_add_f32_e32 v60, 1.0, v60
	v_mul_f32_e32 v62, v62, v66
	v_mul_f32_e32 v63, v63, v66
	v_rcp_f32_e32 v60, v60
	v_add_f32_e32 v61, 1.0, v61
	v_exp_f32_e32 v62, v62
	v_exp_f32_e32 v63, v63
	v_add_f32_e32 v49, 1.0, v49
	v_rcp_f32_e32 v61, v61
	v_rcp_f32_e32 v49, v49
	v_add_f32_e32 v62, 1.0, v62
	v_add_f32_e32 v63, 1.0, v63
	v_mul_f32_e32 v50, v50, v60
	v_mul_f32_e32 v53, v59, v53
	v_add_u32_e32 v55, s28, v70
	v_rcp_f32_e32 v62, v62
	v_rcp_f32_e32 v63, v63
	v_mul_f32_e32 v56, v56, v61
	v_mul_f32_e32 v51, v48, v49
	v_cvt_pk_bf16_f32 v48, v50, v56
	v_cvt_pk_bf16_f32 v50, v52, v53
	v_mad_i64_i32 v[52:53], s[30:31], v55, s33, v[116:117]
	v_lshl_add_u64 v[52:53], v[52:53], 0, s[54:55]
	v_lshl_add_u64 v[52:53], v[52:53], 0, v[194:195]
	v_cvt_pk_bf16_f32 v51, v54, v51
	v_lshl_add_u64 v[52:53], v[52:53], 0, v[118:119]
	v_add_u32_e32 v54, 0x90, v136
	v_mul_f32_e32 v57, v57, v62
	v_mul_f32_e32 v58, v58, v63
	v_cvt_pk_bf16_f32 v49, v57, v58
	global_store_dwordx4 v[52:53], v[48:51], off
	s_nop 1
	v_lshl_add_u32 v48, v54, 4, s8
	ds_read_b128 v[48:51], v48
	s_waitcnt lgkmcnt(0)
	v_mov_b32_e32 v52, v49
	v_mov_b32_e32 v53, v50
	v_mov_b32_e32 v49, v51
	v_pk_add_f32 v[48:49], v[52:53], v[48:49]
	s_nop 0
	v_add_f32_e32 v48, v48, v49
	v_fmamk_f32 v48, v48, 0x3a800000, v189
	v_cmp_gt_f32_e32 vcc, s24, v48
	v_mul_f32_e32 v49, 0x4b800000, v48
	s_nop 0
	v_cndmask_b32_e32 v48, v48, v49, vcc
	v_rsq_f32_e32 v48, v48
	s_nop 0
	v_mul_f32_e32 v49, 0x45800000, v48
	v_cndmask_b32_e32 v49, v48, v49, vcc
	v_mul_f32_e32 v50, 0xbfb8aa3b, v49
	v_mul_f32_e32 v32, v32, v50
	v_exp_f32_e32 v32, v32
	v_mul_f32_e32 v40, v40, v50
	v_exp_f32_e32 v40, v40
	v_mul_f32_e32 v41, v41, v50
	v_add_f32_e32 v32, 1.0, v32
	v_rcp_f32_e32 v51, v32
	v_mul_f32_e32 v32, v33, v50
	v_exp_f32_e32 v41, v41
	v_mul_f32_e32 v42, v42, v50
	v_exp_f32_e32 v32, v32
	v_exp_f32_e32 v42, v42
	v_mul_f32_e32 v43, v43, v50
	v_mov_b32_e32 v48, v34
	v_mul_f32_e32 v34, v34, v50
	v_exp_f32_e32 v43, v43
	v_exp_f32_e32 v34, v34
	v_add_f32_e32 v40, 1.0, v40
	v_rcp_f32_e32 v40, v40
	v_add_f32_e32 v41, 1.0, v41
	v_add_f32_e32 v32, 1.0, v32
	v_rcp_f32_e32 v41, v41
	v_add_f32_e32 v42, 1.0, v42
	v_rcp_f32_e32 v52, v32
	v_mov_b32_e32 v32, v38
	v_mov_b32_e32 v33, v49
	v_rcp_f32_e32 v42, v42
	v_add_f32_e32 v43, 1.0, v43
	v_pk_mul_f32 v[32:33], v[48:49], v[32:33]
	v_add_f32_e32 v34, 1.0, v34
	v_rcp_f32_e32 v43, v43
	v_mul_f32_e32 v38, v44, v33
	v_rcp_f32_e32 v34, v34
	v_mul_f32_e32 v38, v38, v40
	v_mul_f32_e32 v40, v45, v33
	v_mul_f32_e32 v40, v40, v41
	v_mul_f32_e32 v41, v46, v33
	v_mul_f32_e32 v41, v41, v42
	v_mul_f32_e32 v42, v47, v33
	v_mul_f32_e32 v32, v32, v33
	v_mul_f32_e32 v42, v42, v43
	v_mul_f32_e32 v43, v32, v34
	v_mul_f32_e32 v32, v35, v39
	v_mul_f32_e32 v36, v36, v33
	v_mul_f32_e32 v37, v37, v33
	v_mul_f32_e32 v32, v32, v33
	v_mul_f32_e32 v33, v35, v50
	v_exp_f32_e32 v33, v33
	v_mul_f32_e32 v36, v36, v51
	v_mul_f32_e32 v37, v37, v52
	v_add_u32_e32 v39, s28, v54
	v_add_f32_e32 v33, 1.0, v33
	v_rcp_f32_e32 v33, v33
	v_cvt_pk_bf16_f32 v34, v36, v37
	v_mad_i64_i32 v[36:37], s[30:31], v39, s33, v[116:117]
	v_lshl_add_u64 v[36:37], v[36:37], 0, s[54:55]
	v_lshl_add_u64 v[36:37], v[36:37], 0, v[194:195]
	v_mul_f32_e32 v35, v32, v33
	v_cvt_pk_bf16_f32 v32, v38, v40
	v_lshl_add_u64 v[36:37], v[36:37], 0, v[118:119]
	v_add_u32_e32 v38, 0xa0, v136
	v_cvt_pk_bf16_f32 v33, v41, v42
	v_cvt_pk_bf16_f32 v35, v43, v35
	global_store_dwordx4 v[36:37], v[32:35], off
	s_nop 1
	v_lshl_add_u32 v32, v38, 4, s8
	ds_read_b128 v[32:35], v32
	s_waitcnt lgkmcnt(0)
; #define LAS __attribute__((address_space(3)))
; DEV u32x4 pack8(const float (&v)[8]) { u32x4 w; w.x = cvt_pk_bf16(v[0], v[1]); w.y = cvt_pk_bf16(v[2], v[3]); w.z = cvt_pk_bf16(v[4], v[5]); w.w = cvt_pk_bf16(v[6], v[7]); return w; }
; #define BAR __builtin_amdgcn_s_barrier()
; template <int BMODE, class Epi, class TileFn>
; DEV void gemm_loop(LAS unsigned char* lds, const bf16_t* __restrict__ A, int lda, const bf16_t* __restrict__ B, int ldb, int K, const Epi& epi, int t0, int tstep, int tend, const TileFn& tf) {
;     ...
;         if (!has_next) break;
; #pragma unroll
;         for (int a = 0; a < 2; ++a)
; #pragma unroll
;             for (int b = 0; b < 2; ++b)
; #pragma unroll
;                 for (int m = 0; m < 4; ++m)
; #pragma unroll
;                     for (int n = 0; n < 2; ++n) acc[a][b][m][n] = (f32x4){0.f, 0.f, 0.f, 0.f};
;         brow = nrow; bcol = ncol; cA = nA; cB = nB;
;         if (wr == 1) BAR;
;     DEV void operator()(f32x4 (&acc)[2][2][4][2], int brow, int bcol, LAS unsigned char* lds, int par) const {
;     ...
; #pragma unroll
;         for (int ai = 0; ai < 2; ++ai)
; #pragma unroll
;             for (int m = 0; m < 4; ++m) {
;                 const int lr = ai * 128 + wr * 64 + m * 16 + fr, row = brow + lr;
;                 const f32x4 s4 = *(const LAS f32x4*)(lds + LDS_EX + par * 4096 + lr * 16);
;                 const float rs = rsqrtf(((s4[0] + s4[1]) + (s4[2] + s4[3])) * (1.0f / 1024.0f) + EPS);
;                 float o[8];
;                 const float rs2 = rs * rs, ce = rs * -1.4426950408889634f;
; #pragma unroll
;                 for (int bj = 0; bj < 2; ++bj) {
;                     const f32x4 g = acc[ai][bj][m][0], u = acc[ai][bj][m][1];
; #pragma unroll
;                     for (int j = 0; j < 4; ++j) o[bj * 4 + j] = (g[j] * u[j]) * rs2 * __builtin_amdgcn_rcpf(1.0f + __builtin_amdgcn_exp2f(g[j] * ce));
;                 }
;                 *(u32x4*)(act + (size_t)row * DFF + (bcol >> 1) + wc * 32 + fq * 8) = pack8(o);
	v_mov_b32_e32 v36, v33
	v_mov_b32_e32 v37, v34
	v_mov_b32_e32 v33, v35
	v_pk_add_f32 v[32:33], v[36:37], v[32:33]
	v_mul_f32_e32 v35, v20, v16
	v_add_f32_e32 v32, v32, v33
	v_fmamk_f32 v32, v32, 0x3a800000, v189
	v_cmp_gt_f32_e32 vcc, s24, v32
	v_mul_f32_e32 v33, 0x4b800000, v32
	v_mul_f32_e32 v36, v21, v17
	v_cndmask_b32_e32 v32, v32, v33, vcc
	v_rsq_f32_e32 v32, v32
	s_nop 0
	v_mul_f32_e32 v33, 0x45800000, v32
	v_cndmask_b32_e32 v33, v32, v33, vcc
	v_mul_f32_e32 v34, 0xbfb8aa3b, v33
	v_mul_f32_e32 v16, v20, v34
	v_exp_f32_e32 v16, v16
	v_mov_b32_e32 v32, v22
	v_mul_f32_e32 v22, v22, v34
	v_exp_f32_e32 v22, v22
	v_add_f32_e32 v16, 1.0, v16
	v_rcp_f32_e32 v20, v16
	v_mul_f32_e32 v16, v21, v34
	v_exp_f32_e32 v16, v16
	v_add_f32_e32 v22, 1.0, v22
	v_rcp_f32_e32 v22, v22
	v_mov_b32_e32 v17, v33
	v_add_f32_e32 v16, 1.0, v16
	v_rcp_f32_e32 v21, v16
	v_mov_b32_e32 v16, v18
	v_pk_mul_f32 v[16:17], v[32:33], v[16:17]
	v_mul_f32_e32 v28, v28, v34
	v_mul_f32_e32 v16, v16, v17
	v_mul_f32_e32 v18, v24, v17
	v_mul_f32_e32 v24, v25, v17
	v_mul_f32_e32 v25, v26, v17
	v_mul_f32_e32 v26, v27, v17
	v_mul_f32_e32 v27, v35, v17
	v_mul_f32_e32 v22, v16, v22
	v_mul_f32_e32 v16, v23, v19
	v_exp_f32_e32 v28, v28
	v_mul_f32_e32 v29, v29, v34
	v_mul_f32_e32 v20, v27, v20
	v_mul_f32_e32 v27, v36, v17
	v_mul_f32_e32 v16, v16, v17
	v_mul_f32_e32 v17, v23, v34
	v_exp_f32_e32 v29, v29
	v_exp_f32_e32 v17, v17
	v_add_f32_e32 v28, 1.0, v28
	v_mul_f32_e32 v30, v30, v34
	v_mul_f32_e32 v31, v31, v34
	v_rcp_f32_e32 v28, v28
	v_add_f32_e32 v29, 1.0, v29
	v_exp_f32_e32 v30, v30
	v_exp_f32_e32 v31, v31
	v_add_f32_e32 v17, 1.0, v17
	v_rcp_f32_e32 v29, v29
	v_rcp_f32_e32 v17, v17
	v_add_f32_e32 v30, 1.0, v30
	v_add_f32_e32 v31, 1.0, v31
	v_mul_f32_e32 v18, v18, v28
	v_mul_f32_e32 v21, v27, v21
	v_add_u32_e32 v23, s28, v38
	v_rcp_f32_e32 v30, v30
	v_rcp_f32_e32 v31, v31
	v_mul_f32_e32 v24, v24, v29
	v_mul_f32_e32 v19, v16, v17
	v_cvt_pk_bf16_f32 v16, v18, v24
	v_cvt_pk_bf16_f32 v18, v20, v21
	v_mad_i64_i32 v[20:21], s[30:31], v23, s33, v[116:117]
	v_lshl_add_u64 v[20:21], v[20:21], 0, s[54:55]
	v_lshl_add_u64 v[20:21], v[20:21], 0, v[194:195]
	v_cvt_pk_bf16_f32 v19, v22, v19
	v_lshl_add_u64 v[20:21], v[20:21], 0, v[118:119]
	v_add_u32_e32 v22, 0xb0, v136
	v_mul_f32_e32 v25, v25, v30
	v_mul_f32_e32 v26, v26, v31
	v_cvt_pk_bf16_f32 v17, v25, v26
	global_store_dwordx4 v[20:21], v[16:19], off
	s_nop 1
	v_lshl_add_u32 v16, v22, 4, s8
	ds_read_b128 v[16:19], v16
	s_waitcnt lgkmcnt(0)
	v_mov_b32_e32 v20, v17
	v_mov_b32_e32 v21, v18
	v_mov_b32_e32 v17, v19
	v_pk_add_f32 v[16:17], v[20:21], v[16:17]
	s_nop 0
	v_add_f32_e32 v16, v16, v17
	v_fmamk_f32 v16, v16, 0x3a800000, v189
	v_cmp_gt_f32_e32 vcc, s24, v16
	v_mul_f32_e32 v17, 0x4b800000, v16
	s_nop 0
	v_cndmask_b32_e32 v16, v16, v17, vcc
	v_rsq_f32_e32 v16, v16
	s_nop 0
	v_mul_f32_e32 v17, 0x45800000, v16
	v_cndmask_b32_e32 v17, v16, v17, vcc
	v_mul_f32_e32 v18, 0xbfb8aa3b, v17
	v_mul_f32_e32 v0, v0, v18
	v_exp_f32_e32 v0, v0
	v_mul_f32_e32 v8, v8, v18
	v_exp_f32_e32 v8, v8
	v_mul_f32_e32 v9, v9, v18
	v_add_f32_e32 v0, 1.0, v0
	v_rcp_f32_e32 v19, v0
	v_mul_f32_e32 v0, v1, v18
	v_exp_f32_e32 v9, v9
	v_mul_f32_e32 v10, v10, v18
	v_exp_f32_e32 v0, v0
	v_exp_f32_e32 v10, v10
	v_mul_f32_e32 v11, v11, v18
	v_mov_b32_e32 v16, v2
	v_mul_f32_e32 v2, v2, v18
	v_exp_f32_e32 v11, v11
	v_exp_f32_e32 v2, v2
	v_add_f32_e32 v8, 1.0, v8
	v_rcp_f32_e32 v8, v8
	v_add_f32_e32 v9, 1.0, v9
	v_add_f32_e32 v0, 1.0, v0
	v_rcp_f32_e32 v9, v9
	v_add_f32_e32 v10, 1.0, v10
	v_rcp_f32_e32 v20, v0
	v_mov_b32_e32 v0, v6
	v_mov_b32_e32 v1, v17
	v_rcp_f32_e32 v10, v10
	v_add_f32_e32 v11, 1.0, v11
	v_pk_mul_f32 v[0:1], v[16:17], v[0:1]
	v_add_f32_e32 v2, 1.0, v2
	v_rcp_f32_e32 v11, v11
	v_mul_f32_e32 v6, v12, v1
	v_rcp_f32_e32 v2, v2
	v_mul_f32_e32 v6, v6, v8
	v_mul_f32_e32 v8, v13, v1
	v_mul_f32_e32 v8, v8, v9
	v_mul_f32_e32 v9, v14, v1
	v_mul_f32_e32 v9, v9, v10
	v_mul_f32_e32 v10, v15, v1
	v_mul_f32_e32 v0, v0, v1
	v_mul_f32_e32 v10, v10, v11
	v_mul_f32_e32 v11, v0, v2
	v_mul_f32_e32 v0, v3, v7
	v_mul_f32_e32 v4, v4, v1
	v_mul_f32_e32 v5, v5, v1
	v_mul_f32_e32 v0, v0, v1
	v_mul_f32_e32 v1, v3, v18
	v_exp_f32_e32 v1, v1
	v_mul_f32_e32 v4, v4, v19
	v_mul_f32_e32 v5, v5, v20
	v_add_u32_e32 v7, s28, v22
	v_add_f32_e32 v1, 1.0, v1
	v_rcp_f32_e32 v1, v1
	v_cvt_pk_bf16_f32 v2, v4, v5
	v_mad_i64_i32 v[4:5], s[8:9], v7, s33, v[116:117]
	v_lshl_add_u64 v[4:5], v[4:5], 0, s[54:55]
	v_lshl_add_u64 v[4:5], v[4:5], 0, v[194:195]
	v_mul_f32_e32 v3, v0, v1
	v_lshl_add_u64 v[4:5], v[4:5], 0, v[118:119]
	s_mov_b64 s[8:9], -1
	s_andn2_b64 vcc, exec, s[76:77]
	v_cvt_pk_bf16_f32 v0, v6, v8
	v_cvt_pk_bf16_f32 v1, v9, v10
	v_cvt_pk_bf16_f32 v3, v11, v3
	global_store_dwordx4 v[4:5], v[0:3], off
	s_cbranch_vccnz .LBB0_1332
	s_and_saveexec_b64 s[8:9], s[38:39]
	s_cbranch_execz .LBB0_1331
	s_barrier
	s_setprio 1
	s_branch .LBB0_1331

; #define BAR __builtin_amdgcn_s_barrier()
; template <int BMODE, class Epi, class TileFn>
; DEV void gemm_loop(LAS unsigned char* lds, const bf16_t* __restrict__ A, int lda, const bf16_t* __restrict__ B, int ldb, int K, const Epi& epi, int t0, int tstep, int tend, const TileFn& tf) {
;     ...
;         if (!has_next) break;
; #pragma unroll
;         for (int a = 0; a < 2; ++a)
; #pragma unroll
;             for (int b = 0; b < 2; ++b)
; #pragma unroll
;                 for (int m = 0; m < 4; ++m)
; #pragma unroll
;                     for (int n = 0; n < 2; ++n) acc[a][b][m][n] = (f32x4){0.f, 0.f, 0.f, 0.f};
;         brow = nrow; bcol = ncol; cA = nA; cB = nB;
;         if (wr == 1) BAR;
;     }
.LBB0_1462:
	s_or_b64 exec, exec, s[0:1]
	s_andn2_b64 vcc, exec, s[44:45]
	s_mov_b64 s[0:1], -1
	s_cbranch_vccnz .LBB0_1437
	s_and_saveexec_b64 s[0:1], s[38:39]
	s_xor_b64 s[0:1], exec, s[0:1]
	s_cbranch_execz .LBB0_1436
	s_barrier
	s_setprio 1
	s_branch .LBB0_1436
